# P7 rows: the 4 row-1 loads hipcc issued mid-body are issued at the top of the trip with the other 8 (free registers), copied in at the original wait points
# baseline (speedup 1.0000x reference)
.LBB0_1202:
	s_ashr_i32 s1, s0, 31
	s_mul_i32 s10, s0, 0x2c00
	s_mul_hi_i32 s11, s0, 0x2c00
	s_add_u32 s10, s4, s10
	s_addc_u32 s11, s5, s11
	v_lshl_add_u64 v[16:17], s[10:11], 0, v[36:37]
	s_lshl_b64 s[16:17], s[0:1], 11
	v_add_co_u32_e32 v20, vcc, 0x2000, v16
	v_lshl_add_u64 v[18:19], v[38:39], 0, s[16:17]
	s_nop 0
	v_addc_co_u32_e32 v21, vcc, 0, v17, vcc
	global_load_dwordx4 v[50:53], v[20:21], off
	global_load_dwordx4 v[24:27], v[18:19], off offset:1024
	v_add_co_u32_e32 v20, vcc, s13, v16
	global_load_dwordx4 v[46:49], v[18:19], off
	s_nop 0
	v_addc_co_u32_e32 v21, vcc, 0, v17, vcc
	global_load_dwordx4 v[42:45], v[20:21], off offset:2048
	v_lshl_add_u64 v[20:21], v[16:17], 0, s[6:7]
	v_lshl_add_u64 v[16:17], v[16:17], 0, s[8:9]
	global_load_dwordx4 v[32:35], v[16:17], off offset:1024
	s_waitcnt lgkmcnt(0)
	global_load_dwordx4 v[28:31], v[20:21], off offset:1024
	s_add_i32 s15, s0, s83
	s_min_i32 s0, s15, 0xffff
	s_ashr_i32 s1, s0, 31
	s_mul_i32 s16, s0, 0x2c00
	s_mul_hi_i32 s17, s0, 0x2c00
	s_add_u32 s16, s4, s16
	s_addc_u32 s17, s5, s17
	v_lshl_add_u64 v[54:55], s[16:17], 0, v[36:37]
	v_add_co_u32_e32 v58, vcc, s12, v54
	s_lshl_b64 s[0:1], s[0:1], 11
	s_nop 0
	v_addc_co_u32_e32 v59, vcc, 0, v55, vcc
	v_add_co_u32_e32 v60, vcc, s13, v54
	s_cmp_gt_i32 s15, 0xffff
	s_nop 0
	v_addc_co_u32_e32 v61, vcc, 0, v55, vcc
	global_load_dwordx4 v[16:19], v[58:59], off
	global_load_dwordx4 v[20:23], v[60:61], off offset:2048
	v_lshl_add_u64 v[96:97], v[38:39], 0, s[0:1]
	global_load_dwordx4 v[80:83], v[96:97], off
	v_lshl_add_u64 v[98:99], v[54:55], 0, s[6:7]
	global_load_dwordx4 v[84:87], v[98:99], off offset:1024
	v_lshl_add_u64 v[98:99], v[54:55], 0, s[8:9]
	global_load_dwordx4 v[88:91], v[98:99], off offset:1024
	global_load_dwordx4 v[92:95], v[96:97], off offset:1024
	s_waitcnt vmcnt(4)
	v_lshlrev_b32_e32 v70, 16, v50
	v_and_b32_e32 v71, 0xffff0000, v50
	v_lshlrev_b32_e32 v50, 16, v51
	v_and_b32_e32 v51, 0xffff0000, v51
	v_lshlrev_b32_e32 v58, 16, v46
	v_and_b32_e32 v59, 0xffff0000, v46
	v_lshlrev_b32_e32 v46, 16, v47
	v_and_b32_e32 v47, 0xffff0000, v47
	v_lshlrev_b32_e32 v60, 16, v48
	v_and_b32_e32 v61, 0xffff0000, v48
	v_lshlrev_b32_e32 v72, 16, v52
	v_and_b32_e32 v73, 0xffff0000, v52
	v_lshlrev_b32_e32 v74, 16, v42
	v_and_b32_e32 v75, 0xffff0000, v42
	v_lshlrev_b32_e32 v42, 16, v43
	v_and_b32_e32 v43, 0xffff0000, v43
	v_pk_add_f32 v[46:47], v[50:51], v[46:47]
	v_lshlrev_b32_e32 v50, 16, v44
	v_and_b32_e32 v51, 0xffff0000, v44
	v_pk_add_f32 v[58:59], v[70:71], v[58:59]
	v_pk_add_f32 v[60:61], v[72:73], v[60:61]
	v_lshlrev_b32_e32 v70, 16, v45
	v_and_b32_e32 v71, 0xffff0000, v45
	v_mul_f32_e32 v44, 0xbfb8aa3b, v74
	v_mul_f32_e32 v45, 0xbfb8aa3b, v75
	v_mul_f32_e32 v48, 0xbfb8aa3b, v42
	v_mul_f32_e32 v56, 0xbfb8aa3b, v43
	v_mul_f32_e32 v72, 0xbfb8aa3b, v50
	v_mul_f32_e32 v73, 0xbfb8aa3b, v51
	v_exp_f32_e32 v44, v44
	v_exp_f32_e32 v45, v45
	v_exp_f32_e32 v48, v48
	v_exp_f32_e32 v56, v56
	v_exp_f32_e32 v72, v72
	v_exp_f32_e32 v73, v73
	v_add_f32_e32 v44, 1.0, v44
	v_add_f32_e32 v45, 1.0, v45
	v_add_f32_e32 v48, 1.0, v48
	v_add_f32_e32 v56, 1.0, v56
	v_add_f32_e32 v76, 1.0, v72
	v_add_f32_e32 v77, 1.0, v73
	v_rcp_f32_e32 v44, v44
	v_rcp_f32_e32 v45, v45
	v_rcp_f32_e32 v72, v48
	v_rcp_f32_e32 v73, v56
	v_rcp_f32_e32 v76, v76
	v_rcp_f32_e32 v77, v77
	v_mul_f32_e32 v78, 0xbfb8aa3b, v70
	v_pk_mul_f32 v[44:45], v[44:45], v[74:75]
	v_pk_mul_f32 v[72:73], v[72:73], v[42:43]
	v_pk_mul_f32 v[50:51], v[76:77], v[50:51]
	v_exp_f32_e32 v48, v78
	v_pk_mul_f32 v[42:43], v[58:59], v[44:45]
	v_pk_mul_f32 v[44:45], v[46:47], v[72:73]
	v_pk_mul_f32 v[46:47], v[60:61], v[50:51]
	v_mul_f32_e32 v50, 0xbfb8aa3b, v71
	v_exp_f32_e32 v51, v50
	v_add_f32_e32 v48, 1.0, v48
	v_rcp_f32_e32 v50, v48
	v_lshlrev_b32_e32 v52, 16, v53
	v_add_f32_e32 v48, 1.0, v51
	v_rcp_f32_e32 v51, v48
	v_and_b32_e32 v53, 0xffff0000, v53
	v_lshlrev_b32_e32 v48, 16, v49
	v_and_b32_e32 v49, 0xffff0000, v49
	v_pk_add_f32 v[48:49], v[52:53], v[48:49]
	v_lshlrev_b32_e32 v52, 16, v32
	v_pk_mul_f32 v[50:51], v[50:51], v[70:71]
	v_and_b32_e32 v53, 0xffff0000, v32
	v_mul_f32_e32 v32, 0xbfb8aa3b, v52
	v_pk_mul_f32 v[48:49], v[48:49], v[50:51]
	v_exp_f32_e32 v32, v32
	v_mul_f32_e32 v51, 0xbfb8aa3b, v53
	v_exp_f32_e32 v56, v51
	v_lshlrev_b32_e32 v50, 16, v28
	v_and_b32_e32 v51, 0xffff0000, v28
	v_add_f32_e32 v28, 1.0, v32
	v_rcp_f32_e32 v58, v28
	v_add_f32_e32 v28, 1.0, v56
	v_rcp_f32_e32 v59, v28
	v_lshlrev_b32_e32 v60, 16, v24
	v_and_b32_e32 v61, 0xffff0000, v24
	v_lshlrev_b32_e32 v32, 16, v33
	v_pk_add_f32 v[50:51], v[50:51], v[60:61]
	v_pk_mul_f32 v[52:53], v[58:59], v[52:53]
	v_and_b32_e32 v33, 0xffff0000, v33
	v_mul_f32_e32 v24, 0xbfb8aa3b, v32
	v_pk_mul_f32 v[50:51], v[50:51], v[52:53]
	v_exp_f32_e32 v24, v24
	v_mul_f32_e32 v52, 0xbfb8aa3b, v33
	v_exp_f32_e32 v53, v52
	v_lshlrev_b32_e32 v28, 16, v29
	v_add_f32_e32 v24, 1.0, v24
	v_rcp_f32_e32 v52, v24
	v_add_f32_e32 v24, 1.0, v53
	v_rcp_f32_e32 v53, v24
	v_and_b32_e32 v29, 0xffff0000, v29
	v_lshlrev_b32_e32 v24, 16, v25
	v_and_b32_e32 v25, 0xffff0000, v25
	v_pk_add_f32 v[24:25], v[28:29], v[24:25]
	v_pk_mul_f32 v[28:29], v[52:53], v[32:33]
	v_lshlrev_b32_e32 v58, 16, v26
	v_pk_mul_f32 v[52:53], v[24:25], v[28:29]
	v_lshlrev_b32_e32 v28, 16, v34
	v_and_b32_e32 v29, 0xffff0000, v34
	v_mul_f32_e32 v25, 0xbfb8aa3b, v28
	v_exp_f32_e32 v32, v25
	v_mul_f32_e32 v25, 0xbfb8aa3b, v29
	v_exp_f32_e32 v33, v25
	v_lshlrev_b32_e32 v24, 16, v30
	v_and_b32_e32 v25, 0xffff0000, v30
	v_add_f32_e32 v30, 1.0, v32
	v_rcp_f32_e32 v32, v30
	v_add_f32_e32 v30, 1.0, v33
	v_rcp_f32_e32 v33, v30
	v_and_b32_e32 v59, 0xffff0000, v26
	v_pk_add_f32 v[24:25], v[24:25], v[58:59]
	v_pk_mul_f32 v[28:29], v[32:33], v[28:29]
	s_nop 0
	v_pk_mul_f32 v[58:59], v[24:25], v[28:29]
	v_lshlrev_b32_e32 v28, 16, v35
	v_and_b32_e32 v29, 0xffff0000, v35
	v_mul_f32_e32 v25, 0xbfb8aa3b, v28
	v_exp_f32_e32 v26, v25
	v_mul_f32_e32 v25, 0xbfb8aa3b, v29
	v_exp_f32_e32 v32, v25
	v_lshlrev_b32_e32 v24, 16, v31
	v_add_f32_e32 v26, 1.0, v26
	v_rcp_f32_e32 v30, v26
	v_add_f32_e32 v26, 1.0, v32
	v_and_b32_e32 v25, 0xffff0000, v31
	v_rcp_f32_e32 v31, v26
	v_lshlrev_b32_e32 v26, 16, v27
	v_and_b32_e32 v27, 0xffff0000, v27
	v_pk_add_f32 v[24:25], v[24:25], v[26:27]
	v_pk_mul_f32 v[26:27], v[30:31], v[28:29]
	v_mov_b32_e32 v28, v47
	v_pk_mul_f32 v[74:75], v[24:25], v[26:27]
	v_mov_b32_e32 v26, v43
	v_mov_b32_e32 v27, v45
	v_mov_b32_e32 v24, v42
	v_mov_b32_e32 v25, v44
	v_pk_mul_f32 v[26:27], v[26:27], v[26:27]
	v_mov_b32_e32 v29, v49
	v_pk_fma_f32 v[24:25], v[24:25], v[24:25], v[26:27]
	v_mov_b32_e32 v26, v46
	v_pk_add_f32 v[24:25], v[24:25], v[24:25] op_sel_hi:[0,1]
	v_mov_b32_e32 v27, v48
	v_pk_mul_f32 v[28:29], v[28:29], v[28:29]
	v_mul_f32_e32 v24, v50, v50
	v_pk_fma_f32 v[26:27], v[26:27], v[26:27], v[28:29]
	v_pk_fma_f32 v[28:29], v[50:51], v[50:51], v[24:25] op_sel_hi:[1,1,0]
	v_mul_f32_e32 v24, v52, v52
	v_pk_add_f32 v[26:27], v[26:27], v[26:27] op_sel_hi:[0,1]
	v_pk_fma_f32 v[30:31], v[52:53], v[52:53], v[24:25] op_sel_hi:[1,1,0]
	v_pk_mul_f32 v[32:33], v[58:59], v[58:59]
	v_pk_mul_f32 v[34:35], v[74:75], v[74:75]
	v_mov_b32_e32 v24, v32
	v_mov_b32_e32 v26, v33
	v_mov_b32_e32 v28, v34
	v_mov_b32_e32 v30, v35
	v_pk_add_f32 v[24:25], v[24:25], v[26:27]
	v_pk_add_f32 v[26:27], v[28:29], v[30:31]
	s_nop 0
	v_pk_add_f32 v[24:25], v[24:25], v[26:27]
	s_nop 0
	v_add_f32_e32 v24, v24, v25
	ds_bpermute_b32 v25, v57, v24
	s_waitcnt lgkmcnt(0)
	v_add_f32_e32 v24, v24, v25
	ds_bpermute_b32 v25, v62, v24
	s_waitcnt lgkmcnt(0)
	v_add_f32_e32 v24, v24, v25
	ds_bpermute_b32 v25, v63, v24
	s_waitcnt lgkmcnt(0)
	v_add_f32_e32 v24, v24, v25
	ds_bpermute_b32 v25, v64, v24
	s_waitcnt lgkmcnt(0)
	v_add_f32_e32 v24, v24, v25
	ds_bpermute_b32 v25, v65, v24
	s_waitcnt lgkmcnt(0)
	v_add_f32_e32 v24, v24, v25
	ds_bpermute_b32 v25, v66, v24
	s_waitcnt lgkmcnt(0)
	v_add_f32_e32 v24, v24, v25
	v_fmamk_f32 v24, v24, 0x3a800000, v67
	v_mul_f32_e32 v25, 0x4f800000, v24
	v_cmp_gt_f32_e32 vcc, s14, v24
	s_nop 1
	v_cndmask_b32_e32 v30, v24, v25, vcc
	v_sqrt_f32_e32 v31, v30
	s_nop 0
	s_nop 0
	v_add_u32_e32 v32, -1, v31
	v_fma_f32 v33, -v32, v31, v30
	v_cmp_ge_f32_e64 s[0:1], 0, v33
	v_add_u32_e32 v33, 1, v31
	s_waitcnt vmcnt(3)
	v_mov_b32_e32 v70, v80
	v_mov_b32_e32 v71, v81
	v_mov_b32_e32 v72, v82
	v_mov_b32_e32 v73, v83
	v_lshlrev_b32_e32 v78, 16, v70
	v_cndmask_b32_e64 v32, v31, v32, s[0:1]
	v_fma_f32 v31, -v33, v31, v30
	v_cmp_lt_f32_e64 s[0:1], 0, v31
	v_and_b32_e32 v79, 0xffff0000, v70
	s_nop 0
	v_cndmask_b32_e64 v31, v32, v33, s[0:1]
	v_mul_f32_e32 v32, 0x37800000, v31
	v_cndmask_b32_e32 v31, v31, v32, vcc
	v_cmp_class_f32_e32 vcc, v30, v68
	s_nop 0
	s_nop 0
	v_cndmask_b32_e32 v56, v31, v30, vcc
	s_nop 0
	v_div_scale_f32 v60, s[0:1], v56, v56, 1.0
	v_rcp_f32_e32 v61, v60
	s_nop 0
	v_fma_f32 v54, -v60, v61, 1.0
	v_fmac_f32_e32 v61, v54, v61
	v_div_scale_f32 v54, vcc, 1.0, v56, 1.0
	v_mul_f32_e32 v55, v54, v61
	v_fma_f32 v76, -v60, v55, v54
	v_fmac_f32_e32 v55, v76, v61
	v_fma_f32 v54, -v60, v55, v54
	v_div_fmas_f32 v54, v54, v61, v55
	v_div_fixup_f32 v56, v54, v56, 1.0
	v_pk_mul_f32 v[54:55], v[74:75], v[56:57] op_sel_hi:[1,0]
	v_lshlrev_b32_e32 v74, 16, v20
	v_and_b32_e32 v75, 0xffff0000, v20
	v_mul_f32_e32 v20, 0xbfb8aa3b, v74
	v_pk_mul_f32 v[60:61], v[58:59], v[56:57] op_sel_hi:[1,0]
	v_exp_f32_e32 v20, v20
	v_mul_f32_e32 v59, 0xbfb8aa3b, v75
	v_exp_f32_e32 v77, v59
	v_lshlrev_b32_e32 v58, 16, v16
	v_and_b32_e32 v59, 0xffff0000, v16
	v_add_f32_e32 v16, 1.0, v20
	v_rcp_f32_e32 v76, v16
	v_add_f32_e32 v16, 1.0, v77
	v_rcp_f32_e32 v77, v16
	v_lshlrev_b32_e32 v20, 16, v21
	v_pk_add_f32 v[58:59], v[58:59], v[78:79]
	v_and_b32_e32 v21, 0xffff0000, v21
	v_pk_mul_f32 v[74:75], v[76:77], v[74:75]
	v_mul_f32_e32 v70, 0xbfb8aa3b, v20
	v_pk_mul_f32 v[58:59], v[58:59], v[74:75]
	v_exp_f32_e32 v70, v70
	v_mul_f32_e32 v74, 0xbfb8aa3b, v21
	v_exp_f32_e32 v75, v74
	v_lshlrev_b32_e32 v16, 16, v17
	v_add_f32_e32 v70, 1.0, v70
	v_rcp_f32_e32 v74, v70
	v_add_f32_e32 v70, 1.0, v75
	v_rcp_f32_e32 v75, v70
	v_and_b32_e32 v17, 0xffff0000, v17
	v_lshlrev_b32_e32 v70, 16, v71
	v_and_b32_e32 v71, 0xffff0000, v71
	v_pk_add_f32 v[16:17], v[16:17], v[70:71]
	v_pk_mul_f32 v[20:21], v[74:75], v[20:21]
	v_lshlrev_b32_e32 v70, 16, v22
	v_pk_mul_f32 v[16:17], v[16:17], v[20:21]
	v_and_b32_e32 v71, 0xffff0000, v22
	v_mul_f32_e32 v21, 0xbfb8aa3b, v70
	v_exp_f32_e32 v22, v21
	v_mul_f32_e32 v21, 0xbfb8aa3b, v71
	v_exp_f32_e32 v75, v21
	v_lshlrev_b32_e32 v20, 16, v18
	v_and_b32_e32 v21, 0xffff0000, v18
	v_add_f32_e32 v18, 1.0, v22
	v_rcp_f32_e32 v74, v18
	v_add_f32_e32 v18, 1.0, v75
	v_rcp_f32_e32 v75, v18
	v_lshlrev_b32_e32 v76, 16, v72
	v_and_b32_e32 v77, 0xffff0000, v72
	v_pk_add_f32 v[20:21], v[20:21], v[76:77]
	v_pk_mul_f32 v[70:71], v[74:75], v[70:71]
	v_lshlrev_b32_e32 v22, 16, v23
	v_and_b32_e32 v23, 0xffff0000, v23
	v_pk_mul_f32 v[20:21], v[20:21], v[70:71]
	v_mul_f32_e32 v70, 0xbfb8aa3b, v22
	v_mul_f32_e32 v71, 0xbfb8aa3b, v23
	v_exp_f32_e32 v70, v70
	v_exp_f32_e32 v71, v71
	v_lshlrev_b32_e32 v18, 16, v19
	v_and_b32_e32 v19, 0xffff0000, v19
	v_add_f32_e32 v70, 1.0, v70
	v_add_f32_e32 v71, 1.0, v71
	v_rcp_f32_e32 v70, v70
	v_rcp_f32_e32 v71, v71
	v_lshlrev_b32_e32 v72, 16, v73
	v_and_b32_e32 v73, 0xffff0000, v73
	v_pk_add_f32 v[18:19], v[18:19], v[72:73]
	v_pk_mul_f32 v[22:23], v[70:71], v[22:23]
	s_waitcnt vmcnt(1)
	v_mov_b32_e32 v24, v84
	v_mov_b32_e32 v25, v85
	v_mov_b32_e32 v26, v86
	v_mov_b32_e32 v27, v87
	v_mov_b32_e32 v32, v88
	v_mov_b32_e32 v33, v89
	v_mov_b32_e32 v34, v90
	v_mov_b32_e32 v35, v91
	v_lshlrev_b32_e32 v70, 16, v32
	v_pk_mul_f32 v[18:19], v[18:19], v[22:23]
	v_and_b32_e32 v71, 0xffff0000, v32
	v_mul_f32_e32 v23, 0xbfb8aa3b, v70
	v_exp_f32_e32 v32, v23
	v_mul_f32_e32 v23, 0xbfb8aa3b, v71
	v_exp_f32_e32 v73, v23
	v_lshlrev_b32_e32 v22, 16, v24
	v_and_b32_e32 v23, 0xffff0000, v24
	v_add_f32_e32 v24, 1.0, v32
	v_rcp_f32_e32 v72, v24
	v_add_f32_e32 v24, 1.0, v73
	v_rcp_f32_e32 v73, v24
	s_waitcnt vmcnt(0)
	v_mov_b32_e32 v28, v92
	v_mov_b32_e32 v29, v93
	v_mov_b32_e32 v30, v94
	v_mov_b32_e32 v31, v95
	v_lshlrev_b32_e32 v74, 16, v28
	v_and_b32_e32 v75, 0xffff0000, v28
	v_lshlrev_b32_e32 v32, 16, v33
	v_pk_add_f32 v[22:23], v[22:23], v[74:75]
	v_pk_mul_f32 v[70:71], v[72:73], v[70:71]
	v_and_b32_e32 v33, 0xffff0000, v33
	v_mul_f32_e32 v28, 0xbfb8aa3b, v32
	v_pk_mul_f32 v[22:23], v[22:23], v[70:71]
	v_exp_f32_e32 v28, v28
	v_mul_f32_e32 v70, 0xbfb8aa3b, v33
	v_exp_f32_e32 v71, v70
	v_lshlrev_b32_e32 v24, 16, v25
	v_add_f32_e32 v28, 1.0, v28
	v_rcp_f32_e32 v70, v28
	v_add_f32_e32 v28, 1.0, v71
	v_rcp_f32_e32 v71, v28
	v_and_b32_e32 v25, 0xffff0000, v25
	v_lshlrev_b32_e32 v28, 16, v29
	v_and_b32_e32 v29, 0xffff0000, v29
	v_pk_add_f32 v[24:25], v[24:25], v[28:29]
	v_pk_mul_f32 v[28:29], v[70:71], v[32:33]
	v_lshlrev_b32_e32 v32, 16, v34
	v_pk_mul_f32 v[24:25], v[24:25], v[28:29]
	v_and_b32_e32 v33, 0xffff0000, v34
	v_mul_f32_e32 v29, 0xbfb8aa3b, v32
	v_exp_f32_e32 v34, v29
	v_mul_f32_e32 v29, 0xbfb8aa3b, v33
	v_exp_f32_e32 v71, v29
	v_lshlrev_b32_e32 v28, 16, v26
	v_and_b32_e32 v29, 0xffff0000, v26
	v_add_f32_e32 v26, 1.0, v34
	v_rcp_f32_e32 v70, v26
	v_add_f32_e32 v26, 1.0, v71
	v_rcp_f32_e32 v71, v26
	v_lshlrev_b32_e32 v72, 16, v30
	v_and_b32_e32 v73, 0xffff0000, v30
	v_pk_add_f32 v[28:29], v[28:29], v[72:73]
	v_pk_mul_f32 v[32:33], v[70:71], v[32:33]
	v_lshlrev_b32_e32 v26, 16, v27
	v_pk_mul_f32 v[28:29], v[28:29], v[32:33]
	v_lshlrev_b32_e32 v32, 16, v35
	v_and_b32_e32 v33, 0xffff0000, v35
	v_mul_f32_e32 v30, 0xbfb8aa3b, v32
	v_exp_f32_e32 v30, v30
	v_mul_f32_e32 v34, 0xbfb8aa3b, v33
	v_exp_f32_e32 v35, v34
	v_and_b32_e32 v27, 0xffff0000, v27
	v_add_f32_e32 v30, 1.0, v30
	v_rcp_f32_e32 v34, v30
	v_add_f32_e32 v30, 1.0, v35
	v_rcp_f32_e32 v35, v30
	v_lshlrev_b32_e32 v30, 16, v31
	v_and_b32_e32 v31, 0xffff0000, v31
	v_pk_add_f32 v[26:27], v[26:27], v[30:31]
	v_pk_mul_f32 v[30:31], v[34:35], v[32:33]
	v_pk_mul_f32 v[32:33], v[16:17], v[16:17]
	v_pk_mul_f32 v[26:27], v[26:27], v[30:31]
	v_pk_mul_f32 v[30:31], v[58:59], v[58:59]
	v_pk_mul_f32 v[34:35], v[20:21], v[20:21]
	v_pk_mul_f32 v[70:71], v[18:19], v[18:19]
	v_pk_mul_f32 v[72:73], v[22:23], v[22:23]
	v_pk_mul_f32 v[74:75], v[24:25], v[24:25]
	v_add_f32_e32 v70, v70, v71
	v_add_f32_e32 v34, v34, v35
	v_add_f32_e32 v32, v32, v33
	v_add_f32_e32 v30, v30, v31
	v_add_f32_e32 v34, v34, v70
	v_add_f32_e32 v30, v30, v32
	v_add_f32_e32 v31, v74, v75
	v_add_f32_e32 v32, v72, v73
	v_pk_mul_f32 v[76:77], v[28:29], v[28:29]
	v_pk_mul_f32 v[78:79], v[26:27], v[26:27]
	v_add_f32_e32 v30, v30, v34
	v_add_f32_e32 v31, v32, v31
	v_add_f32_e32 v30, v30, v31
	v_add_f32_e32 v31, v78, v79
	v_add_f32_e32 v32, v76, v77
	v_add_f32_e32 v31, v32, v31
	v_add_f32_e32 v70, v31, v30
	ds_bpermute_b32 v71, v57, v70
	v_pk_mul_f32 v[34:35], v[12:13], v[60:61]
	v_pk_mul_f32 v[32:33], v[52:53], v[56:57] op_sel_hi:[1,0]
	v_pk_mul_f32 v[30:31], v[50:51], v[56:57] op_sel_hi:[1,0]
	v_pk_mul_f32 v[50:51], v[10:11], v[32:33]
	s_waitcnt lgkmcnt(0)
	v_add_f32_e32 v60, v70, v71
	ds_bpermute_b32 v61, v62, v60
	v_pk_mul_f32 v[32:33], v[48:49], v[56:57] op_sel_hi:[1,0]
	v_pk_mul_f32 v[52:53], v[8:9], v[30:31]
	v_pk_mul_f32 v[30:31], v[46:47], v[56:57] op_sel_hi:[1,0]
	v_pk_mul_f32 v[46:47], v[6:7], v[32:33]
	s_waitcnt lgkmcnt(0)
	v_add_f32_e32 v48, v60, v61
	ds_bpermute_b32 v49, v63, v48
	v_pk_mul_f32 v[32:33], v[4:5], v[30:31]
	v_pk_mul_f32 v[30:31], v[42:43], v[56:57] op_sel_hi:[1,0]
	v_pk_mul_f32 v[42:43], v[44:45], v[56:57] op_sel_hi:[1,0]
	v_pk_mul_f32 v[30:31], v[0:1], v[30:31]
	s_waitcnt lgkmcnt(0)
	v_add_f32_e32 v44, v48, v49
	ds_bpermute_b32 v45, v64, v44
	v_pk_mul_f32 v[42:43], v[2:3], v[42:43]
	v_cvt_pk_bf16_f32 v30, v30, v31
	v_pk_mul_f32 v[54:55], v[14:15], v[54:55]
	v_cvt_pk_bf16_f32 v31, v42, v43
	s_waitcnt lgkmcnt(0)
	v_add_f32_e32 v42, v44, v45
	ds_bpermute_b32 v43, v65, v42
	v_cvt_pk_bf16_f32 v32, v32, v33
	v_cvt_pk_bf16_f32 v33, v46, v47
	global_store_dwordx4 v36, v[30:33], s[10:11] offset:2048
	s_waitcnt lgkmcnt(0)
	s_nop 0
	v_add_f32_e32 v30, v42, v43
	ds_bpermute_b32 v31, v66, v30
	v_cvt_pk_bf16_f32 v32, v52, v53
	v_cvt_pk_bf16_f32 v33, v50, v51
	v_cvt_pk_bf16_f32 v34, v34, v35
	v_cvt_pk_bf16_f32 v35, v54, v55
	global_store_dwordx4 v36, v[32:35], s[10:11] offset:3072
	s_cbranch_scc1 .LBB0_1201
	s_waitcnt lgkmcnt(0)
	v_add_f32_e32 v30, v30, v31
	v_fmamk_f32 v30, v30, 0x3a800000, v67
	v_mul_f32_e32 v31, 0x4f800000, v30
	v_cmp_gt_f32_e32 vcc, s14, v30
	s_nop 1
	v_cndmask_b32_e32 v30, v30, v31, vcc
	v_sqrt_f32_e32 v31, v30
	s_nop 0
	v_add_u32_e32 v32, -1, v31
	v_fma_f32 v34, -v32, v31, v30
	v_add_u32_e32 v33, 1, v31
	v_cmp_ge_f32_e64 s[0:1], 0, v34
	s_nop 1
	v_cndmask_b32_e64 v32, v31, v32, s[0:1]
	v_fma_f32 v31, -v33, v31, v30
	v_cmp_lt_f32_e64 s[0:1], 0, v31
	s_nop 1
	v_cndmask_b32_e64 v31, v32, v33, s[0:1]
	v_mul_f32_e32 v32, 0x37800000, v31
	v_cndmask_b32_e32 v31, v31, v32, vcc
	v_cmp_class_f32_e32 vcc, v30, v68
	s_nop 1
	v_cndmask_b32_e32 v30, v31, v30, vcc
	v_div_scale_f32 v31, s[0:1], v30, v30, 1.0
	v_rcp_f32_e32 v32, v31
	s_nop 0
	v_fma_f32 v33, -v31, v32, 1.0
	v_fmac_f32_e32 v32, v33, v32
	v_div_scale_f32 v33, vcc, 1.0, v30, 1.0
	v_mul_f32_e32 v34, v33, v32
	v_fma_f32 v35, -v31, v34, v33
	v_fmac_f32_e32 v34, v35, v32
	v_fma_f32 v31, -v31, v34, v33
	v_div_fmas_f32 v31, v31, v32, v34
	v_div_fixup_f32 v30, v31, v30, 1.0
	v_pk_mul_f32 v[20:21], v[20:21], v[30:31] op_sel_hi:[1,0]
	v_pk_mul_f32 v[18:19], v[18:19], v[30:31] op_sel_hi:[1,0]
	v_pk_mul_f32 v[16:17], v[16:17], v[30:31] op_sel_hi:[1,0]
	v_pk_mul_f32 v[32:33], v[6:7], v[18:19]
	v_pk_mul_f32 v[18:19], v[4:5], v[20:21]
	v_pk_mul_f32 v[20:21], v[58:59], v[30:31] op_sel_hi:[1,0]
	v_pk_mul_f32 v[28:29], v[28:29], v[30:31] op_sel_hi:[1,0]
	v_pk_mul_f32 v[26:27], v[26:27], v[30:31] op_sel_hi:[1,0]
	v_pk_mul_f32 v[22:23], v[22:23], v[30:31] op_sel_hi:[1,0]
	v_pk_mul_f32 v[24:25], v[24:25], v[30:31] op_sel_hi:[1,0]
	v_pk_mul_f32 v[30:31], v[2:3], v[16:17]
	v_pk_mul_f32 v[16:17], v[0:1], v[20:21]
	v_mad_i64_i32 v[20:21], s[0:1], s15, v69, v[40:41]
	v_cvt_pk_bf16_f32 v16, v16, v17
	v_cvt_pk_bf16_f32 v17, v30, v31
	v_cvt_pk_bf16_f32 v18, v18, v19
	v_cvt_pk_bf16_f32 v19, v32, v33
	v_pk_mul_f32 v[26:27], v[14:15], v[26:27]
	v_pk_mul_f32 v[28:29], v[12:13], v[28:29]
	v_pk_mul_f32 v[24:25], v[10:11], v[24:25]
	v_pk_mul_f32 v[22:23], v[8:9], v[22:23]
	global_store_dwordx4 v[20:21], v[16:19], off offset:2048
	s_nop 1
	v_cvt_pk_bf16_f32 v16, v22, v23
	v_cvt_pk_bf16_f32 v17, v24, v25
	v_cvt_pk_bf16_f32 v18, v28, v29
	v_cvt_pk_bf16_f32 v19, v26, v27
	global_store_dwordx4 v[20:21], v[16:19], off offset:3072
	s_branch .LBB0_1201
